# mixers epilogues (attn O/NSA/gMLP -> BR): 8-byte store pairs merged via v_permlane32_swap into 16-byte sc1 stores
# baseline (speedup 1.0000x reference)
.LBB0_1670:
	s_waitcnt lgkmcnt(0)
	v_add_f32_e32 v0, v194, v195
	v_max_f32_e32 v0, 0xda24260, v0
	s_waitcnt vmcnt(0)
	v_div_scale_f32 v2, s[0:1], v0, v0, v173
	v_rcp_f32_e32 v3, v2
	s_barrier
	v_fma_f32 v4, -v2, v3, 1.0
	v_fmac_f32_e32 v3, v4, v3
	v_div_scale_f32 v4, vcc, v173, v0, v173
	v_mul_f32_e32 v5, v4, v3
	v_fma_f32 v6, -v2, v5, v4
	v_fmac_f32_e32 v5, v6, v3
	v_fma_f32 v2, -v2, v5, v4
	v_div_fmas_f32 v2, v2, v3, v5
	v_div_fixup_f32 v0, v2, v0, v173
	v_mov_b32_e32 v2, v1
	v_pk_mul_f32 v[8:9], v[16:17], v[190:191] op_sel_hi:[1,0]
	v_mbcnt_lo_u32_b32 v2, -1, v2
	v_mbcnt_hi_u32_b32 v2, -1, v2
	v_lshlrev_b32_e32 v2, 2, v2
	v_xor_b32_e32 v2, 0x80, v2
	ds_bpermute_b32 v2, v2, v196
	v_pk_mul_f32 v[10:11], v[34:35], v[190:191] op_sel_hi:[1,0]
	v_pk_mul_f32 v[12:13], v[18:19], v[190:191] op_sel_hi:[1,0]
	v_pk_mul_f32 v[14:15], v[36:37], v[190:191] op_sel_hi:[1,0]
	v_pk_mul_f32 v[16:17], v[20:21], v[190:191] op_sel_hi:[1,0]
	s_waitcnt lgkmcnt(0)
	v_add_f32_e32 v2, v196, v2
	v_max_f32_e32 v2, 0xda24260, v2
	v_div_scale_f32 v3, s[0:1], v2, v2, v174
	v_rcp_f32_e32 v4, v3
	v_pk_mul_f32 v[18:19], v[38:39], v[190:191] op_sel_hi:[1,0]
	v_pk_mul_f32 v[20:21], v[22:23], v[190:191] op_sel_hi:[1,0]
	v_pk_mul_f32 v[22:23], v[40:41], v[190:191] op_sel_hi:[1,0]
	v_fma_f32 v5, -v3, v4, 1.0
	v_fmac_f32_e32 v4, v5, v4
	v_div_scale_f32 v5, vcc, v174, v2, v174
	v_mul_f32_e32 v6, v5, v4
	v_fma_f32 v7, -v3, v6, v5
	v_fmac_f32_e32 v6, v7, v4
	v_fma_f32 v3, -v3, v6, v5
	v_div_fmas_f32 v3, v3, v4, v6
	v_pk_mul_f32 v[4:5], v[64:65], v[0:1] op_sel_hi:[1,0]
	v_pk_mul_f32 v[6:7], v[32:33], v[190:191] op_sel_hi:[1,0]
	v_pk_mul_f32 v[24:25], v[24:25], v[190:191] op_sel_hi:[1,0]
	v_pk_fma_f32 v[4:5], v[172:173], v[6:7], v[4:5] op_sel_hi:[0,1,1]
	v_pk_mul_f32 v[6:7], v[48:49], v[0:1] op_sel_hi:[1,0]
	v_pk_mul_f32 v[32:33], v[42:43], v[190:191] op_sel_hi:[1,0]
	v_pk_fma_f32 v[6:7], v[172:173], v[8:9], v[6:7] op_sel_hi:[0,1,1]
	v_pk_mul_f32 v[8:9], v[66:67], v[0:1] op_sel_hi:[1,0]
	v_pk_mul_f32 v[26:27], v[26:27], v[190:191] op_sel_hi:[1,0]
	v_pk_fma_f32 v[8:9], v[172:173], v[10:11], v[8:9] op_sel_hi:[0,1,1]
	v_pk_mul_f32 v[10:11], v[50:51], v[0:1] op_sel_hi:[1,0]
	v_pk_mul_f32 v[34:35], v[44:45], v[190:191] op_sel_hi:[1,0]
	v_pk_fma_f32 v[10:11], v[172:173], v[12:13], v[10:11] op_sel_hi:[0,1,1]
	v_pk_mul_f32 v[12:13], v[68:69], v[0:1] op_sel_hi:[1,0]
	v_pk_mul_f32 v[28:29], v[28:29], v[190:191] op_sel_hi:[1,0]
	v_pk_fma_f32 v[12:13], v[172:173], v[14:15], v[12:13] op_sel_hi:[0,1,1]
	v_pk_mul_f32 v[14:15], v[52:53], v[0:1] op_sel_hi:[1,0]
	v_pk_mul_f32 v[36:37], v[46:47], v[190:191] op_sel_hi:[1,0]
	v_pk_fma_f32 v[14:15], v[172:173], v[16:17], v[14:15] op_sel_hi:[0,1,1]
	v_pk_mul_f32 v[16:17], v[70:71], v[0:1] op_sel_hi:[1,0]
	v_pk_mul_f32 v[30:31], v[30:31], v[190:191] op_sel_hi:[1,0]
	v_pk_fma_f32 v[16:17], v[172:173], v[18:19], v[16:17] op_sel_hi:[0,1,1]
	v_pk_mul_f32 v[18:19], v[54:55], v[0:1] op_sel_hi:[1,0]
	v_div_fixup_f32 v2, v3, v2, v174
	v_pk_fma_f32 v[18:19], v[172:173], v[20:21], v[18:19] op_sel_hi:[0,1,1]
	v_pk_mul_f32 v[20:21], v[72:73], v[0:1] op_sel_hi:[1,0]
	v_readlane_b32 s0, v255, 1
	v_pk_fma_f32 v[20:21], v[172:173], v[22:23], v[20:21] op_sel_hi:[0,1,1]
	v_pk_mul_f32 v[22:23], v[56:57], v[0:1] op_sel_hi:[1,0]
	v_pk_fma_f32 v[4:5], v[96:97], v[2:3], v[4:5] op_sel_hi:[1,0,1]
	v_pk_fma_f32 v[22:23], v[172:173], v[24:25], v[22:23] op_sel_hi:[0,1,1]
	v_pk_mul_f32 v[24:25], v[74:75], v[0:1] op_sel_hi:[1,0]
	v_pk_fma_f32 v[6:7], v[80:81], v[2:3], v[6:7] op_sel_hi:[1,0,1]
	v_pk_fma_f32 v[24:25], v[172:173], v[32:33], v[24:25] op_sel_hi:[0,1,1]
	v_pk_mul_f32 v[32:33], v[58:59], v[0:1] op_sel_hi:[1,0]
	v_pk_fma_f32 v[8:9], v[98:99], v[2:3], v[8:9] op_sel_hi:[1,0,1]
	v_pk_fma_f32 v[26:27], v[172:173], v[26:27], v[32:33] op_sel_hi:[0,1,1]
	v_pk_mul_f32 v[32:33], v[76:77], v[0:1] op_sel_hi:[1,0]
	v_pk_fma_f32 v[10:11], v[82:83], v[2:3], v[10:11] op_sel_hi:[1,0,1]
	v_pk_fma_f32 v[32:33], v[172:173], v[34:35], v[32:33] op_sel_hi:[0,1,1]
	v_pk_mul_f32 v[34:35], v[60:61], v[0:1] op_sel_hi:[1,0]
	v_pk_fma_f32 v[12:13], v[100:101], v[2:3], v[12:13] op_sel_hi:[1,0,1]
	v_pk_fma_f32 v[28:29], v[172:173], v[28:29], v[34:35] op_sel_hi:[0,1,1]
	v_pk_mul_f32 v[34:35], v[78:79], v[0:1] op_sel_hi:[1,0]
	v_pk_fma_f32 v[14:15], v[84:85], v[2:3], v[14:15] op_sel_hi:[1,0,1]
	v_pk_fma_f32 v[34:35], v[172:173], v[36:37], v[34:35] op_sel_hi:[0,1,1]
	v_pk_mul_f32 v[36:37], v[62:63], v[0:1] op_sel_hi:[1,0]
	v_pk_fma_f32 v[16:17], v[102:103], v[2:3], v[16:17] op_sel_hi:[1,0,1]
	v_pk_fma_f32 v[30:31], v[172:173], v[30:31], v[36:37] op_sel_hi:[0,1,1]
	v_pk_fma_f32 v[18:19], v[86:87], v[2:3], v[18:19] op_sel_hi:[1,0,1]
	v_pk_fma_f32 v[20:21], v[104:105], v[2:3], v[20:21] op_sel_hi:[1,0,1]
	v_pk_fma_f32 v[22:23], v[88:89], v[2:3], v[22:23] op_sel_hi:[1,0,1]
	v_pk_fma_f32 v[24:25], v[106:107], v[2:3], v[24:25] op_sel_hi:[1,0,1]
	v_pk_fma_f32 v[26:27], v[90:91], v[2:3], v[26:27] op_sel_hi:[1,0,1]
	v_pk_fma_f32 v[32:33], v[108:109], v[2:3], v[32:33] op_sel_hi:[1,0,1]
	v_pk_fma_f32 v[28:29], v[92:93], v[2:3], v[28:29] op_sel_hi:[1,0,1]
	v_pk_fma_f32 v[34:35], v[110:111], v[2:3], v[34:35] op_sel_hi:[1,0,1]
	v_pk_fma_f32 v[2:3], v[94:95], v[2:3], v[30:31] op_sel_hi:[1,0,1]
	v_lshlrev_b64 v[30:31], 11, v[186:187]
	v_readlane_b32 s1, v255, 2
	v_lshlrev_b32_e32 v0, 1, v189
	v_cvt_pk_bf16_f32 v4, v4, v5
	v_lshl_add_u64 v[30:31], s[0:1], 0, v[30:31]
	v_lshl_add_u64 v[30:31], v[30:31], 0, v[0:1]
	v_lshlrev_b32_e32 v0, 3, v191
	v_lshl_add_u64 v[30:31], v[30:31], 0, v[0:1]
	s_mov_b64 s[0:1], 0x8a00400
	v_lshl_add_u64 v[36:37], v[30:31], 0, s[0:1]
	s_mov_b32 s0, 0x8a00000
	v_cvt_pk_bf16_f32 v5, v8, v9
	v_add_co_u32_e32 v8, vcc, s0, v30
	v_cvt_pk_bf16_f32 v6, v6, v7
	s_nop 0
	v_addc_co_u32_e32 v9, vcc, 0, v31, vcc
	v_cvt_pk_bf16_f32 v7, v10, v11
	v_mov_b32_e32 v240, v4
	v_mov_b32_e32 v241, v5
	v_mov_b32_e32 v244, v6
	v_mov_b32_e32 v245, v7
	v_cvt_pk_bf16_f32 v4, v12, v13
	v_cvt_pk_bf16_f32 v5, v16, v17
	v_cvt_pk_bf16_f32 v6, v14, v15
	v_cvt_pk_bf16_f32 v7, v18, v19
	v_mov_b32_e32 v242, v4
	v_mov_b32_e32 v243, v5
	v_mbcnt_lo_u32_b32 v222, -1, 0
	v_mbcnt_hi_u32_b32 v222, -1, v222
	v_lshrrev_b32_e32 v222, 5, v222
	v_lshlrev_b32_e32 v222, 3, v222
	v_mov_b32_e32 v223, 0
	v_permlane32_swap_b32_e32 v240, v242
	v_permlane32_swap_b32_e32 v241, v243
	v_lshl_add_u64 v[222:223], v[36:37], 0, v[222:223]
	global_store_dwordx4 v[222:223], v[240:243], off sc1
	v_mov_b32_e32 v246, v6
	v_mov_b32_e32 v247, v7
	v_mbcnt_lo_u32_b32 v222, -1, 0
	v_mbcnt_hi_u32_b32 v222, -1, v222
	v_lshrrev_b32_e32 v222, 5, v222
	v_lshlrev_b32_e32 v222, 3, v222
	v_mov_b32_e32 v223, 0
	v_permlane32_swap_b32_e32 v244, v246
	v_permlane32_swap_b32_e32 v245, v247
	v_lshl_add_u64 v[222:223], v[36:37], 0, v[222:223]
	global_store_dwordx4 v[222:223], v[244:247], off offset:64 sc1
	v_cvt_pk_bf16_f32 v4, v20, v21
	v_cvt_pk_bf16_f32 v5, v24, v25
	v_cvt_pk_bf16_f32 v6, v22, v23
	v_cvt_pk_bf16_f32 v7, v26, v27
	v_mov_b32_e32 v240, v4
	v_mov_b32_e32 v241, v5
	v_mov_b32_e32 v244, v6
	v_mov_b32_e32 v245, v7
	v_cvt_pk_bf16_f32 v4, v32, v33
	v_cvt_pk_bf16_f32 v5, v34, v35
	s_mov_b64 s[4:5], 0
	v_cvt_pk_bf16_f32 v6, v28, v29
	v_cvt_pk_bf16_f32 v7, v2, v3
	v_mov_b32_e32 v242, v4
	v_mov_b32_e32 v243, v5
	v_mbcnt_lo_u32_b32 v222, -1, 0
	v_mbcnt_hi_u32_b32 v222, -1, v222
	v_lshrrev_b32_e32 v222, 5, v222
	v_lshlrev_b32_e32 v222, 3, v222
	v_mov_b32_e32 v223, 0
	v_permlane32_swap_b32_e32 v240, v242
	v_permlane32_swap_b32_e32 v241, v243
	v_lshl_add_u64 v[222:223], v[36:37], 0, v[222:223]
	global_store_dwordx4 v[222:223], v[240:243], off offset:32 sc1
	v_mov_b32_e32 v246, v6
	v_mov_b32_e32 v247, v7
	v_mbcnt_lo_u32_b32 v222, -1, 0
	v_mbcnt_hi_u32_b32 v222, -1, v222
	v_lshrrev_b32_e32 v222, 5, v222
	v_lshlrev_b32_e32 v222, 3, v222
	v_mov_b32_e32 v223, 0
	v_permlane32_swap_b32_e32 v244, v246
	v_permlane32_swap_b32_e32 v245, v247
	v_lshl_add_u64 v[222:223], v[36:37], 0, v[222:223]
	global_store_dwordx4 v[222:223], v[244:247], off offset:96 sc1
	s_barrier

.LBB0_1707:
	s_or_b64 exec, exec, s[12:13]
	v_mov_b32_e32 v0, v1
	s_mov_b32 s9, s95
	v_mbcnt_lo_u32_b32 v0, -1, v0
	v_mbcnt_hi_u32_b32 v0, -1, v0
	v_lshlrev_b32_e32 v0, 2, v0
	v_xor_b32_e32 v0, 0x80, v0
	ds_bpermute_b32 v0, v0, v129
	s_waitcnt lgkmcnt(0)
	v_add_f32_e32 v0, v129, v0
	v_max_f32_e32 v0, 0xda24260, v0
	v_div_scale_f32 v2, s[0:1], v0, v0, 1.0
	v_rcp_f32_e32 v3, v2
	s_mov_b64 s[0:1], 0x8a00200
	v_fma_f32 v4, -v2, v3, 1.0
	v_fmac_f32_e32 v3, v4, v3
	v_div_scale_f32 v4, vcc, 1.0, v0, 1.0
	v_mul_f32_e32 v5, v4, v3
	v_fma_f32 v6, -v2, v5, v4
	v_fmac_f32_e32 v5, v6, v3
	v_fma_f32 v2, -v2, v5, v4
	v_div_fmas_f32 v2, v2, v3, v5
	v_lshlrev_b64 v[4:5], 11, v[108:109]
	v_lshl_add_u64 v[4:5], s[6:7], 0, v[4:5]
	v_div_fixup_f32 v2, v2, v0, 1.0
	v_lshl_add_u64 v[4:5], v[4:5], 0, s[8:9]
	v_lshlrev_b32_e32 v0, 1, v111
	v_lshl_add_u64 v[4:5], v[4:5], 0, v[0:1]
	v_lshl_add_u64 v[6:7], v[4:5], 0, s[0:1]
	s_mov_b32 s0, 0x8a00000
	v_pk_mul_f32 v[8:9], v[32:33], v[2:3] op_sel_hi:[1,0]
	v_pk_mul_f32 v[10:11], v[34:35], v[2:3] op_sel_hi:[1,0]
	v_add_co_u32_e32 v4, vcc, s0, v4
	v_cvt_pk_bf16_f32 v8, v8, v9
	v_cvt_pk_bf16_f32 v9, v10, v11
	v_pk_mul_f32 v[10:11], v[16:17], v[2:3] op_sel_hi:[1,0]
	v_pk_mul_f32 v[12:13], v[18:19], v[2:3] op_sel_hi:[1,0]
	v_addc_co_u32_e32 v5, vcc, 0, v5, vcc
	v_cvt_pk_bf16_f32 v10, v10, v11
	v_cvt_pk_bf16_f32 v11, v12, v13
	v_mov_b32_e32 v240, v8
	v_mov_b32_e32 v241, v9
	v_mov_b32_e32 v244, v10
	v_mov_b32_e32 v245, v11
	v_pk_mul_f32 v[4:5], v[36:37], v[2:3] op_sel_hi:[1,0]
	v_pk_mul_f32 v[8:9], v[38:39], v[2:3] op_sel_hi:[1,0]
	v_cvt_pk_bf16_f32 v4, v4, v5
	v_cvt_pk_bf16_f32 v5, v8, v9
	v_pk_mul_f32 v[8:9], v[20:21], v[2:3] op_sel_hi:[1,0]
	v_pk_mul_f32 v[10:11], v[22:23], v[2:3] op_sel_hi:[1,0]
	v_cvt_pk_bf16_f32 v8, v8, v9
	v_cvt_pk_bf16_f32 v9, v10, v11
	v_mov_b32_e32 v242, v4
	v_mov_b32_e32 v243, v5
	v_mbcnt_lo_u32_b32 v222, -1, 0
	v_mbcnt_hi_u32_b32 v222, -1, v222
	v_lshrrev_b32_e32 v222, 5, v222
	v_lshlrev_b32_e32 v222, 3, v222
	v_mov_b32_e32 v223, 0
	v_permlane32_swap_b32_e32 v240, v242
	v_permlane32_swap_b32_e32 v241, v243
	v_lshl_add_u64 v[222:223], v[6:7], 0, v[222:223]
	global_store_dwordx4 v[222:223], v[240:243], off sc1
	v_mov_b32_e32 v246, v8
	v_mov_b32_e32 v247, v9
	v_mbcnt_lo_u32_b32 v222, -1, 0
	v_mbcnt_hi_u32_b32 v222, -1, v222
	v_lshrrev_b32_e32 v222, 5, v222
	v_lshlrev_b32_e32 v222, 3, v222
	v_mov_b32_e32 v223, 0
	v_permlane32_swap_b32_e32 v244, v246
	v_permlane32_swap_b32_e32 v245, v247
	v_lshl_add_u64 v[222:223], v[6:7], 0, v[222:223]
	global_store_dwordx4 v[222:223], v[244:247], off offset:64 sc1
	v_pk_mul_f32 v[4:5], v[40:41], v[2:3] op_sel_hi:[1,0]
	v_pk_mul_f32 v[8:9], v[42:43], v[2:3] op_sel_hi:[1,0]
	v_cvt_pk_bf16_f32 v4, v4, v5
	v_cvt_pk_bf16_f32 v5, v8, v9
	v_pk_mul_f32 v[8:9], v[24:25], v[2:3] op_sel_hi:[1,0]
	v_pk_mul_f32 v[10:11], v[26:27], v[2:3] op_sel_hi:[1,0]
	v_cvt_pk_bf16_f32 v8, v8, v9
	v_cvt_pk_bf16_f32 v9, v10, v11
	v_mov_b32_e32 v240, v4
	v_mov_b32_e32 v241, v5
	v_mov_b32_e32 v244, v8
	v_mov_b32_e32 v245, v9
	v_pk_mul_f32 v[4:5], v[44:45], v[2:3] op_sel_hi:[1,0]
	v_pk_mul_f32 v[8:9], v[46:47], v[2:3] op_sel_hi:[1,0]
	v_cvt_pk_bf16_f32 v4, v4, v5
	v_cvt_pk_bf16_f32 v5, v8, v9
	v_pk_mul_f32 v[8:9], v[28:29], v[2:3] op_sel_hi:[1,0]
	v_pk_mul_f32 v[2:3], v[30:31], v[2:3] op_sel_hi:[1,0]
	v_cvt_pk_bf16_f32 v8, v8, v9
	v_cvt_pk_bf16_f32 v9, v2, v3
	v_mov_b32_e32 v242, v4
	v_mov_b32_e32 v243, v5
	v_mbcnt_lo_u32_b32 v222, -1, 0
	v_mbcnt_hi_u32_b32 v222, -1, v222
	v_lshrrev_b32_e32 v222, 5, v222
	v_lshlrev_b32_e32 v222, 3, v222
	v_mov_b32_e32 v223, 0
	v_permlane32_swap_b32_e32 v240, v242
	v_permlane32_swap_b32_e32 v241, v243
	v_lshl_add_u64 v[222:223], v[6:7], 0, v[222:223]
	global_store_dwordx4 v[222:223], v[240:243], off offset:32 sc1
	v_mov_b32_e32 v246, v8
	v_mov_b32_e32 v247, v9
	v_mbcnt_lo_u32_b32 v222, -1, 0
	v_mbcnt_hi_u32_b32 v222, -1, v222
	v_lshrrev_b32_e32 v222, 5, v222
	v_lshlrev_b32_e32 v222, 3, v222
	v_mov_b32_e32 v223, 0
	v_permlane32_swap_b32_e32 v244, v246
	v_permlane32_swap_b32_e32 v245, v247
	v_lshl_add_u64 v[222:223], v[6:7], 0, v[222:223]
	global_store_dwordx4 v[222:223], v[244:247], off offset:96 sc1
	s_barrier

.LBB0_1710:
	s_mov_b32 s0, s33
	v_readlane_b32 s1, v254, 30
	v_mov_b32_e32 v0, s0
	ds_read2_b32 v[2:3], v0 offset1:1
	s_ashr_i32 s0, s91, 8
	v_mov_b32_e32 v0, s1
	v_readlane_b32 s1, v254, 31
	ds_read2_b32 v[12:13], v0 offset1:1
	s_and_b32 s22, s91, 3
	v_mov_b32_e32 v0, s1
	s_mov_b32 s1, s33
	ds_read2_b32 v[14:15], v0 offset1:1
	s_waitcnt lgkmcnt(2)
	v_readfirstlane_b32 s2, v2
	v_mov_b32_e32 v0, s1
	ds_read2_b32 v[18:19], v0 offset1:1
	v_mov_b32_e32 v0, v1
	v_readfirstlane_b32 s3, v3
	s_add_u32 s14, s2, 0xaa00000
	s_getreg_b32 s1, hwreg(HW_REG_HW_ID, 0, 6)
	s_addc_u32 s15, s3, 0
	s_lshl_b32 s1, s1, 2
	s_and_b32 s1, s1, 0xfc
	v_add_u32_e32 v2, s1, v0
	v_add_u32_e32 v2, 0x24800, v2
	ds_read_b32 v2, v2
	v_mbcnt_lo_u32_b32 v0, -1, v0
	v_mbcnt_hi_u32_b32 v16, -1, v0
	v_lshlrev_b32_e32 v0, 4, v16
	v_and_b32_e32 v10, 0x70, v0
	s_waitcnt lgkmcnt(0)
	v_readfirstlane_b32 s1, v2
	v_mov_b32_e32 v11, v1
	v_readfirstlane_b32 s17, v19
	v_lshl_add_u32 v17, s1, 6, v16
	s_ashr_i32 s1, s0, 31
	s_lshl_b64 s[18:19], s[0:1], 13
	s_lshl_b32 s0, s91, 5
	s_and_b32 s0, s0, 0x1f80
	s_or_b32 s18, s18, s0
	s_mul_i32 s0, s19, 0x1600
	s_mul_hi_u32 s1, s18, 0x1600
	s_add_i32 s1, s1, s0
	s_mul_i32 s0, s18, 0x1600
	s_add_u32 s0, s14, s0
	s_addc_u32 s1, s15, s1
	s_lshl_b32 s2, s22, 7
	s_add_u32 s0, s0, s2
	s_addc_u32 s1, s1, 0
	v_lshl_add_u64 v[2:3], s[0:1], 0, v[10:11]
	s_mov_b64 s[0:1], 0x1400
	v_add_u32_e32 v0, 0x200, v17
	v_lshl_add_u64 v[2:3], v[2:3], 0, s[0:1]
	v_ashrrev_i32_e32 v11, 3, v17
	s_waitcnt vmcnt(5)
	v_ashrrev_i32_e32 v98, 3, v0
	v_mad_i64_i32 v[4:5], s[0:1], v11, s89, v[2:3]
	v_mad_i64_i32 v[2:3], s[0:1], v98, s89, v[2:3]
	global_load_dwordx4 v[6:9], v[4:5], off
	s_nop 0
	global_load_dwordx4 v[2:5], v[2:3], off
	v_ashrrev_i32_e32 v19, 2, v17
	s_movk_i32 s3, 0xffe0
	v_bfi_b32 v82, s3, v19, v16
	v_readlane_b32 s3, v254, 59
	s_or_b32 s94, s2, s3
	v_ashrrev_i32_e32 v83, 31, v82
	v_readfirstlane_b32 s0, v12
	v_readfirstlane_b32 s1, v13
	v_lshl_add_u64 v[12:13], v[82:83], 0, s[94:95]
	v_readfirstlane_b32 s23, v14
	v_readfirstlane_b32 s24, v15
	v_lshlrev_b64 v[14:15], 9, v[12:13]
	v_bfe_u32 v85, v16, 5, 1
	v_readfirstlane_b32 s16, v18
	v_lshl_add_u64 v[14:15], s[0:1], 0, v[14:15]
	v_or_b32_e32 v18, 31, v19
	v_lshlrev_b32_e32 v0, 5, v85
	v_lshl_add_u64 v[14:15], v[14:15], 0, v[0:1]
	v_cmp_lt_i32_e64 s[12:13], -16, v18
	s_and_saveexec_b64 s[0:1], s[12:13]
	s_cbranch_execz .LBB0_1712
	global_load_dwordx4 v[78:81], v[14:15], off
	global_load_dwordx4 v[74:77], v[14:15], off offset:16

.LBB0_1742:
	s_or_b64 exec, exec, s[0:1]
	v_lshlrev_b64 v[18:19], 11, v[92:93]
	v_lshl_add_u64 v[18:19], s[16:17], 0, v[18:19]
	v_lshlrev_b32_e32 v20, 2, v85
	v_lshl_add_u64 v[18:19], v[18:19], 0, s[94:95]
	v_lshl_add_u64 v[18:19], v[18:19], 0, v[0:1]
	v_lshlrev_b32_e32 v0, 1, v20
	s_waitcnt vmcnt(3)
	v_lshlrev_b32_e32 v22, 16, v94
	v_and_b32_e32 v23, 0xffff0000, v94
	s_nop 1
	v_pk_add_f32 v[2:3], v[84:85], v[2:3] op_sel_hi:[0,1]
	v_lshl_add_u64 v[18:19], v[18:19], 0, v[0:1]
	s_mov_b64 s[0:1], 0x8a00600
	v_pk_mul_f32 v[2:3], v[2:3], v[22:23]
	v_lshlrev_b32_e32 v22, 16, v95
	v_and_b32_e32 v23, 0xffff0000, v95
	v_pk_add_f32 v[4:5], v[84:85], v[4:5] op_sel_hi:[0,1]
	v_lshl_add_u64 v[20:21], v[18:19], 0, s[0:1]
	v_pk_mul_f32 v[4:5], v[4:5], v[22:23]
	s_mov_b32 s0, 0x8a00000
	v_cvt_pk_bf16_f32 v2, v2, v3
	v_cvt_pk_bf16_f32 v3, v4, v5
	v_add_co_u32_e32 v4, vcc, s0, v18
	s_nop 1
	v_addc_co_u32_e32 v5, vcc, 0, v19, vcc
	v_mov_b32_e32 v240, v2
	v_mov_b32_e32 v241, v3
	s_waitcnt vmcnt(2)
	v_lshlrev_b32_e32 v2, 16, v90
	v_and_b32_e32 v3, 0xffff0000, v90
	v_pk_add_f32 v[4:5], v[84:85], v[6:7] op_sel_hi:[0,1]
	v_pk_mul_f32 v[2:3], v[4:5], v[2:3]
	v_lshlrev_b32_e32 v4, 16, v91
	v_and_b32_e32 v5, 0xffff0000, v91
	v_pk_add_f32 v[6:7], v[84:85], v[8:9] op_sel_hi:[0,1]
	v_pk_mul_f32 v[4:5], v[6:7], v[4:5]
	v_cvt_pk_bf16_f32 v2, v2, v3
	v_cvt_pk_bf16_f32 v3, v4, v5
	v_mov_b32_e32 v242, v2
	v_mov_b32_e32 v243, v3
	v_mbcnt_lo_u32_b32 v222, -1, 0
	v_mbcnt_hi_u32_b32 v222, -1, v222
	v_lshrrev_b32_e32 v222, 5, v222
	v_lshlrev_b32_e32 v222, 3, v222
	v_mov_b32_e32 v223, 0
	v_permlane32_swap_b32_e32 v240, v242
	v_permlane32_swap_b32_e32 v241, v243
	v_lshl_add_u64 v[222:223], v[20:21], 0, v[222:223]
	global_store_dwordx4 v[222:223], v[240:243], off sc1
	s_waitcnt vmcnt(2)
	v_lshlrev_b32_e32 v2, 16, v88
	v_and_b32_e32 v3, 0xffff0000, v88
	v_pk_add_f32 v[4:5], v[84:85], v[10:11] op_sel_hi:[0,1]
	v_pk_mul_f32 v[2:3], v[4:5], v[2:3]
	v_lshlrev_b32_e32 v4, 16, v89
	v_and_b32_e32 v5, 0xffff0000, v89
	v_pk_add_f32 v[6:7], v[84:85], v[12:13] op_sel_hi:[0,1]
	v_pk_mul_f32 v[4:5], v[6:7], v[4:5]
	v_cvt_pk_bf16_f32 v2, v2, v3
	v_cvt_pk_bf16_f32 v3, v4, v5
	v_mov_b32_e32 v240, v2
	v_mov_b32_e32 v241, v3
	s_waitcnt vmcnt(1)
	v_lshlrev_b32_e32 v2, 16, v86
	v_and_b32_e32 v3, 0xffff0000, v86
	v_pk_add_f32 v[4:5], v[84:85], v[14:15] op_sel_hi:[0,1]
	v_pk_mul_f32 v[2:3], v[4:5], v[2:3]
	v_lshlrev_b32_e32 v4, 16, v87
	v_and_b32_e32 v5, 0xffff0000, v87
	v_pk_add_f32 v[6:7], v[84:85], v[16:17] op_sel_hi:[0,1]
	v_pk_mul_f32 v[4:5], v[6:7], v[4:5]
	v_cvt_pk_bf16_f32 v2, v2, v3
	v_cvt_pk_bf16_f32 v3, v4, v5
	v_mov_b32_e32 v242, v2
	v_mov_b32_e32 v243, v3
	v_mbcnt_lo_u32_b32 v222, -1, 0
	v_mbcnt_hi_u32_b32 v222, -1, v222
	v_lshrrev_b32_e32 v222, 5, v222
	v_lshlrev_b32_e32 v222, 3, v222
	v_mov_b32_e32 v223, 0
	v_permlane32_swap_b32_e32 v240, v242
	v_permlane32_swap_b32_e32 v241, v243
	v_lshl_add_u64 v[222:223], v[20:21], 0, v[222:223]
	global_store_dwordx4 v[222:223], v[240:243], off offset:32 sc1
	s_barrier
	s_branch .LBB0_1771

.LBB0_1754:
	v_mov_b32_e32 v0, v1
	s_lshl_b32 s94, s3, 1
	v_mbcnt_lo_u32_b32 v0, -1, v0
	v_mbcnt_hi_u32_b32 v0, -1, v0
	v_lshlrev_b32_e32 v0, 2, v0
	v_xor_b32_e32 v0, 0x80, v0
	ds_bpermute_b32 v0, v0, v189
	s_waitcnt lgkmcnt(0)
	v_add_f32_e32 v0, v189, v0
	v_max_f32_e32 v0, 0xda24260, v0
	v_div_scale_f32 v66, s[0:1], v0, v0, 1.0
	v_rcp_f32_e32 v67, v66
	s_nop 0
	v_fma_f32 v68, -v66, v67, 1.0
	v_fmac_f32_e32 v67, v68, v67
	v_div_scale_f32 v68, vcc, 1.0, v0, 1.0
	v_mul_f32_e32 v69, v68, v67
	v_fma_f32 v70, -v66, v69, v68
	v_fmac_f32_e32 v69, v70, v67
	v_fma_f32 v66, -v66, v69, v68
	v_div_fmas_f32 v66, v66, v67, v69
	v_div_fixup_f32 v66, v66, v0, 1.0
	v_mov_b32_e32 v0, v1
	s_nop 0
	v_mbcnt_lo_u32_b32 v0, -1, v0
	v_mbcnt_hi_u32_b32 v0, -1, v0
	v_lshlrev_b32_e32 v0, 2, v0
	v_xor_b32_e32 v0, 0x80, v0
	ds_bpermute_b32 v0, v0, v159
	s_waitcnt lgkmcnt(0)
	v_add_f32_e32 v0, v159, v0
	v_max_f32_e32 v0, 0xda24260, v0
	v_div_scale_f32 v67, s[0:1], v0, v0, v175
	v_rcp_f32_e32 v68, v67
	s_mov_b64 s[0:1], 0x8a00000
	v_fma_f32 v69, -v67, v68, 1.0
	v_fmac_f32_e32 v68, v69, v68
	v_div_scale_f32 v69, vcc, v175, v0, v175
	v_mul_f32_e32 v70, v69, v68
	v_fma_f32 v71, -v67, v70, v69
	v_fmac_f32_e32 v70, v71, v68
	v_fma_f32 v67, -v67, v70, v69
	v_div_fmas_f32 v67, v67, v68, v70
	v_div_fixup_f32 v68, v67, v0, v175
	v_mov_b32_e32 v0, v1
	v_pk_mul_f32 v[44:45], v[44:45], v[68:69] op_sel_hi:[1,0]
	v_mbcnt_lo_u32_b32 v0, -1, v0
	v_pk_mul_f32 v[52:53], v[52:53], v[68:69] op_sel_hi:[1,0]
	v_pk_mul_f32 v[50:51], v[50:51], v[68:69] op_sel_hi:[1,0]
	v_pk_fma_f32 v[28:29], v[28:29], v[66:67], v[44:45] op_sel_hi:[1,0,1] neg_lo:[0,0,1] neg_hi:[0,0,1]
	v_pk_mul_f32 v[44:45], v[60:61], v[68:69] op_sel_hi:[1,0]
	v_mbcnt_hi_u32_b32 v0, -1, v0
	v_lshlrev_b64 v[60:61], 11, v[154:155]
	v_pk_fma_f32 v[4:5], v[4:5], v[66:67], v[52:53] op_sel_hi:[1,0,1] neg_lo:[0,0,1] neg_hi:[0,0,1]
	v_pk_fma_f32 v[2:3], v[2:3], v[66:67], v[50:51] op_sel_hi:[1,0,1] neg_lo:[0,0,1] neg_hi:[0,0,1]
	v_pk_mul_f32 v[36:37], v[36:37], v[68:69] op_sel_hi:[1,0]
	v_pk_mul_f32 v[34:35], v[34:35], v[68:69] op_sel_hi:[1,0]
	v_pk_mul_f32 v[48:49], v[48:49], v[68:69] op_sel_hi:[1,0]
	v_lshlrev_b32_e32 v0, 2, v0
	v_lshl_add_u64 v[60:61], s[4:5], 0, v[60:61]
	v_pk_mul_f32 v[52:53], v[4:5], v[4:5]
	v_pk_mul_f32 v[50:51], v[2:3], v[2:3]
	v_pk_fma_f32 v[20:21], v[20:21], v[66:67], v[36:37] op_sel_hi:[1,0,1] neg_lo:[0,0,1] neg_hi:[0,0,1]
	v_pk_fma_f32 v[18:19], v[18:19], v[66:67], v[34:35] op_sel_hi:[1,0,1] neg_lo:[0,0,1] neg_hi:[0,0,1]
	v_pk_fma_f32 v[32:33], v[32:33], v[66:67], v[48:49] op_sel_hi:[1,0,1] neg_lo:[0,0,1] neg_hi:[0,0,1]
	v_pk_mul_f32 v[48:49], v[64:65], v[68:69] op_sel_hi:[1,0]
	v_xor_b32_e32 v64, 0x80, v0
	v_lshl_add_u64 v[60:61], v[60:61], 0, s[94:95]
	v_lshlrev_b32_e32 v0, 1, v157
	v_pk_fma_f32 v[36:37], v[20:21], v[20:21], v[52:53]
	v_pk_fma_f32 v[34:35], v[18:19], v[18:19], v[50:51]
	v_pk_mul_f32 v[52:53], v[54:55], v[68:69] op_sel_hi:[1,0]
	v_lshl_add_u64 v[60:61], v[60:61], 0, v[0:1]
	v_pk_mul_f32 v[50:51], v[56:57], v[68:69] op_sel_hi:[1,0]
	v_pk_fma_f32 v[6:7], v[6:7], v[66:67], v[52:53] op_sel_hi:[1,0,1] neg_lo:[0,0,1] neg_hi:[0,0,1]
	v_pk_mul_f32 v[38:39], v[38:39], v[68:69] op_sel_hi:[1,0]
	v_add_f32_e32 v0, v34, v35
	v_pk_fma_f32 v[8:9], v[8:9], v[66:67], v[50:51] op_sel_hi:[1,0,1] neg_lo:[0,0,1] neg_hi:[0,0,1]
	v_pk_mul_f32 v[52:53], v[6:7], v[6:7]
	v_pk_mul_f32 v[40:41], v[40:41], v[68:69] op_sel_hi:[1,0]
	v_pk_fma_f32 v[22:23], v[22:23], v[66:67], v[38:39] op_sel_hi:[1,0,1] neg_lo:[0,0,1] neg_hi:[0,0,1]
	v_add_f32_e32 v0, v36, v0
	v_pk_mul_f32 v[50:51], v[8:9], v[8:9]
	v_pk_fma_f32 v[24:25], v[24:25], v[66:67], v[40:41] op_sel_hi:[1,0,1] neg_lo:[0,0,1] neg_hi:[0,0,1]
	v_pk_fma_f32 v[38:39], v[22:23], v[22:23], v[52:53]
	v_add_f32_e32 v0, v37, v0
	v_pk_fma_f32 v[40:41], v[24:25], v[24:25], v[50:51]
	v_pk_mul_f32 v[50:51], v[58:59], v[68:69] op_sel_hi:[1,0]
	v_add_f32_e32 v0, v38, v0
	v_pk_fma_f32 v[10:11], v[10:11], v[66:67], v[50:51] op_sel_hi:[1,0,1] neg_lo:[0,0,1] neg_hi:[0,0,1]
	v_pk_mul_f32 v[42:43], v[42:43], v[68:69] op_sel_hi:[1,0]
	v_add_f32_e32 v0, v39, v0
	v_pk_mul_f32 v[50:51], v[10:11], v[10:11]
	v_pk_fma_f32 v[26:27], v[26:27], v[66:67], v[42:43] op_sel_hi:[1,0,1] neg_lo:[0,0,1] neg_hi:[0,0,1]
	v_add_f32_e32 v0, v40, v0
	v_pk_fma_f32 v[12:13], v[12:13], v[66:67], v[44:45] op_sel_hi:[1,0,1] neg_lo:[0,0,1] neg_hi:[0,0,1]
	v_pk_mul_f32 v[46:47], v[46:47], v[68:69] op_sel_hi:[1,0]
	v_pk_fma_f32 v[42:43], v[26:27], v[26:27], v[50:51]
	v_add_f32_e32 v0, v41, v0
	v_pk_mul_f32 v[44:45], v[12:13], v[12:13]
	v_pk_fma_f32 v[30:31], v[30:31], v[66:67], v[46:47] op_sel_hi:[1,0,1] neg_lo:[0,0,1] neg_hi:[0,0,1]
	v_pk_mul_f32 v[46:47], v[62:63], v[68:69] op_sel_hi:[1,0]
	v_add_f32_e32 v0, v42, v0
	v_pk_fma_f32 v[44:45], v[28:29], v[28:29], v[44:45]
	v_pk_fma_f32 v[14:15], v[14:15], v[66:67], v[46:47] op_sel_hi:[1,0,1] neg_lo:[0,0,1] neg_hi:[0,0,1]
	v_add_f32_e32 v0, v43, v0
	v_pk_mul_f32 v[46:47], v[14:15], v[14:15]
	v_add_f32_e32 v0, v44, v0
	v_pk_fma_f32 v[46:47], v[30:31], v[30:31], v[46:47]
	v_pk_fma_f32 v[16:17], v[16:17], v[66:67], v[48:49] op_sel_hi:[1,0,1] neg_lo:[0,0,1] neg_hi:[0,0,1]
	v_add_f32_e32 v0, v45, v0
	v_pk_mul_f32 v[48:49], v[16:17], v[16:17]
	v_add_f32_e32 v0, v46, v0
	v_pk_fma_f32 v[48:49], v[32:33], v[32:33], v[48:49]
	v_add_f32_e32 v0, v47, v0
	v_add_f32_e32 v0, v48, v0
	v_add_f32_e32 v0, v49, v0
	ds_bpermute_b32 v34, v64, v0
	v_lshl_add_u64 v[62:63], v[60:61], 0, s[0:1]
	s_mov_b32 s0, 0x8a00000
	s_waitcnt lgkmcnt(0)
	v_add_f32_e32 v0, v0, v34
	v_fmamk_f32 v0, v0, 0x3c800000, v228
	v_rsq_f32_e32 v0, v0
	s_nop 0
	v_mul_f32_e32 v0, v185, v0
	v_pk_mul_f32 v[2:3], v[2:3], v[0:1] op_sel_hi:[1,0]
	v_pk_mul_f32 v[4:5], v[4:5], v[0:1] op_sel_hi:[1,0]
	v_pk_mul_f32 v[18:19], v[18:19], v[0:1] op_sel_hi:[1,0]
	v_pk_mul_f32 v[20:21], v[20:21], v[0:1] op_sel_hi:[1,0]
	v_cvt_pk_bf16_f32 v2, v2, v3
	v_cvt_pk_bf16_f32 v3, v4, v5
	v_add_co_u32_e32 v4, vcc, s0, v60
	v_cvt_pk_bf16_f32 v18, v18, v19
	v_cvt_pk_bf16_f32 v19, v20, v21
	v_addc_co_u32_e32 v5, vcc, 0, v61, vcc
	v_mov_b32_e32 v240, v18
	v_mov_b32_e32 v241, v19
	v_mov_b32_e32 v244, v2
	v_mov_b32_e32 v245, v3
	v_pk_mul_f32 v[2:3], v[22:23], v[0:1] op_sel_hi:[1,0]
	v_pk_mul_f32 v[4:5], v[24:25], v[0:1] op_sel_hi:[1,0]
	v_cvt_pk_bf16_f32 v2, v2, v3
	v_cvt_pk_bf16_f32 v3, v4, v5
	v_pk_mul_f32 v[4:5], v[6:7], v[0:1] op_sel_hi:[1,0]
	v_pk_mul_f32 v[6:7], v[8:9], v[0:1] op_sel_hi:[1,0]
	v_cvt_pk_bf16_f32 v4, v4, v5
	v_cvt_pk_bf16_f32 v5, v6, v7
	v_mov_b32_e32 v242, v2
	v_mov_b32_e32 v243, v3
	v_mbcnt_lo_u32_b32 v222, -1, 0
	v_mbcnt_hi_u32_b32 v222, -1, v222
	v_lshrrev_b32_e32 v222, 5, v222
	v_lshlrev_b32_e32 v222, 3, v222
	v_mov_b32_e32 v223, 0
	v_permlane32_swap_b32_e32 v240, v242
	v_permlane32_swap_b32_e32 v241, v243
	v_lshl_add_u64 v[222:223], v[62:63], 0, v[222:223]
	global_store_dwordx4 v[222:223], v[240:243], off sc1
	v_mov_b32_e32 v246, v4
	v_mov_b32_e32 v247, v5
	v_mbcnt_lo_u32_b32 v222, -1, 0
	v_mbcnt_hi_u32_b32 v222, -1, v222
	v_lshrrev_b32_e32 v222, 5, v222
	v_lshlrev_b32_e32 v222, 3, v222
	v_mov_b32_e32 v223, 0
	v_permlane32_swap_b32_e32 v244, v246
	v_permlane32_swap_b32_e32 v245, v247
	v_lshl_add_u64 v[222:223], v[62:63], 0, v[222:223]
	global_store_dwordx4 v[222:223], v[244:247], off offset:64 sc1
	v_pk_mul_f32 v[2:3], v[26:27], v[0:1] op_sel_hi:[1,0]
	v_pk_mul_f32 v[4:5], v[28:29], v[0:1] op_sel_hi:[1,0]
	v_cvt_pk_bf16_f32 v2, v2, v3
	v_cvt_pk_bf16_f32 v3, v4, v5
	v_pk_mul_f32 v[4:5], v[10:11], v[0:1] op_sel_hi:[1,0]
	v_pk_mul_f32 v[6:7], v[12:13], v[0:1] op_sel_hi:[1,0]
	v_cvt_pk_bf16_f32 v4, v4, v5
	v_cvt_pk_bf16_f32 v5, v6, v7
	v_mov_b32_e32 v240, v2
	v_mov_b32_e32 v241, v3
	v_mov_b32_e32 v244, v4
	v_mov_b32_e32 v245, v5
	v_pk_mul_f32 v[2:3], v[30:31], v[0:1] op_sel_hi:[1,0]
	v_pk_mul_f32 v[4:5], v[32:33], v[0:1] op_sel_hi:[1,0]
	v_cvt_pk_bf16_f32 v2, v2, v3
	v_cvt_pk_bf16_f32 v3, v4, v5
	v_pk_mul_f32 v[4:5], v[14:15], v[0:1] op_sel_hi:[1,0]
	v_pk_mul_f32 v[6:7], v[16:17], v[0:1] op_sel_hi:[1,0]
	v_cvt_pk_bf16_f32 v4, v4, v5
	v_cvt_pk_bf16_f32 v5, v6, v7
	v_mov_b32_e32 v242, v2
	v_mov_b32_e32 v243, v3
	v_mbcnt_lo_u32_b32 v222, -1, 0
	v_mbcnt_hi_u32_b32 v222, -1, v222
	v_lshrrev_b32_e32 v222, 5, v222
	v_lshlrev_b32_e32 v222, 3, v222
	v_mov_b32_e32 v223, 0
	v_permlane32_swap_b32_e32 v240, v242
	v_permlane32_swap_b32_e32 v241, v243
	v_lshl_add_u64 v[222:223], v[62:63], 0, v[222:223]
	global_store_dwordx4 v[222:223], v[240:243], off offset:32 sc1
	v_mov_b32_e32 v246, v4
	v_mov_b32_e32 v247, v5
	v_mbcnt_lo_u32_b32 v222, -1, 0
	v_mbcnt_hi_u32_b32 v222, -1, v222
	v_lshrrev_b32_e32 v222, 5, v222
	v_lshlrev_b32_e32 v222, 3, v222
	v_mov_b32_e32 v223, 0
	v_permlane32_swap_b32_e32 v244, v246
	v_permlane32_swap_b32_e32 v245, v247
	v_lshl_add_u64 v[222:223], v[62:63], 0, v[222:223]
	global_store_dwordx4 v[222:223], v[244:247], off offset:96 sc1
	s_barrier
	s_mov_b64 s[0:1], 0

.LBB0_1770:
	v_mov_b32_e32 v0, v1
	s_lshl_b32 s94, s8, 1
	v_mbcnt_lo_u32_b32 v0, -1, v0
	v_mbcnt_hi_u32_b32 v0, -1, v0
	v_lshlrev_b32_e32 v0, 2, v0
	v_xor_b32_e32 v0, 0x80, v0
	ds_bpermute_b32 v0, v0, v189
	s_waitcnt lgkmcnt(0)
	v_add_f32_e32 v0, v189, v0
	v_max_f32_e32 v0, 0xda24260, v0
	v_div_scale_f32 v66, s[0:1], v0, v0, 1.0
	v_rcp_f32_e32 v67, v66
	s_nop 0
	v_fma_f32 v68, -v66, v67, 1.0
	v_fmac_f32_e32 v67, v68, v67
	v_div_scale_f32 v68, vcc, 1.0, v0, 1.0
	v_mul_f32_e32 v69, v68, v67
	v_fma_f32 v70, -v66, v69, v68
	v_fmac_f32_e32 v69, v70, v67
	v_fma_f32 v66, -v66, v69, v68
	v_div_fmas_f32 v66, v66, v67, v69
	v_div_fixup_f32 v66, v66, v0, 1.0
	v_mov_b32_e32 v0, v1
	s_nop 0
	v_mbcnt_lo_u32_b32 v0, -1, v0
	v_mbcnt_hi_u32_b32 v0, -1, v0
	v_lshlrev_b32_e32 v0, 2, v0
	v_xor_b32_e32 v0, 0x80, v0
	ds_bpermute_b32 v0, v0, v159
	s_waitcnt lgkmcnt(0)
	v_add_f32_e32 v0, v159, v0
	v_max_f32_e32 v0, 0xda24260, v0
	v_div_scale_f32 v67, s[0:1], v0, v0, v175
	v_rcp_f32_e32 v68, v67
	s_mov_b64 s[0:1], 0x8a00000
	v_fma_f32 v69, -v67, v68, 1.0
	v_fmac_f32_e32 v68, v69, v68
	v_div_scale_f32 v69, vcc, v175, v0, v175
	v_mul_f32_e32 v70, v69, v68
	v_fma_f32 v71, -v67, v70, v69
	v_fmac_f32_e32 v70, v71, v68
	v_fma_f32 v67, -v67, v70, v69
	v_div_fmas_f32 v67, v67, v68, v70
	v_div_fixup_f32 v68, v67, v0, v175
	v_mov_b32_e32 v0, v1
	v_pk_mul_f32 v[28:29], v[28:29], v[68:69] op_sel_hi:[1,0]
	v_mbcnt_lo_u32_b32 v0, -1, v0
	v_pk_mul_f32 v[52:53], v[52:53], v[68:69] op_sel_hi:[1,0]
	v_pk_mul_f32 v[50:51], v[50:51], v[68:69] op_sel_hi:[1,0]
	v_pk_fma_f32 v[28:29], v[44:45], v[66:67], v[28:29] op_sel_hi:[1,0,1] neg_lo:[0,0,1] neg_hi:[0,0,1]
	v_pk_mul_f32 v[44:45], v[60:61], v[68:69] op_sel_hi:[1,0]
	v_mbcnt_hi_u32_b32 v0, -1, v0
	v_lshlrev_b64 v[60:61], 11, v[154:155]
	v_pk_fma_f32 v[4:5], v[4:5], v[66:67], v[52:53] op_sel_hi:[1,0,1] neg_lo:[0,0,1] neg_hi:[0,0,1]
	v_pk_fma_f32 v[2:3], v[2:3], v[66:67], v[50:51] op_sel_hi:[1,0,1] neg_lo:[0,0,1] neg_hi:[0,0,1]
	v_pk_mul_f32 v[20:21], v[20:21], v[68:69] op_sel_hi:[1,0]
	v_pk_mul_f32 v[18:19], v[18:19], v[68:69] op_sel_hi:[1,0]
	v_pk_mul_f32 v[32:33], v[32:33], v[68:69] op_sel_hi:[1,0]
	v_lshlrev_b32_e32 v0, 2, v0
	v_lshl_add_u64 v[60:61], s[2:3], 0, v[60:61]
	v_pk_mul_f32 v[52:53], v[4:5], v[4:5]
	v_pk_mul_f32 v[50:51], v[2:3], v[2:3]
	v_pk_fma_f32 v[20:21], v[36:37], v[66:67], v[20:21] op_sel_hi:[1,0,1] neg_lo:[0,0,1] neg_hi:[0,0,1]
	v_pk_fma_f32 v[18:19], v[34:35], v[66:67], v[18:19] op_sel_hi:[1,0,1] neg_lo:[0,0,1] neg_hi:[0,0,1]
	v_pk_fma_f32 v[32:33], v[48:49], v[66:67], v[32:33] op_sel_hi:[1,0,1] neg_lo:[0,0,1] neg_hi:[0,0,1]
	v_pk_mul_f32 v[48:49], v[64:65], v[68:69] op_sel_hi:[1,0]
	v_xor_b32_e32 v64, 0x80, v0
	v_lshl_add_u64 v[60:61], v[60:61], 0, s[94:95]
	v_lshlrev_b32_e32 v0, 1, v157
	v_pk_fma_f32 v[36:37], v[20:21], v[20:21], v[52:53]
	v_pk_fma_f32 v[34:35], v[18:19], v[18:19], v[50:51]
	v_pk_mul_f32 v[52:53], v[54:55], v[68:69] op_sel_hi:[1,0]
	v_lshl_add_u64 v[60:61], v[60:61], 0, v[0:1]
	v_pk_mul_f32 v[50:51], v[56:57], v[68:69] op_sel_hi:[1,0]
	v_pk_fma_f32 v[6:7], v[6:7], v[66:67], v[52:53] op_sel_hi:[1,0,1] neg_lo:[0,0,1] neg_hi:[0,0,1]
	v_pk_mul_f32 v[22:23], v[22:23], v[68:69] op_sel_hi:[1,0]
	v_add_f32_e32 v0, v34, v35
	v_pk_fma_f32 v[8:9], v[8:9], v[66:67], v[50:51] op_sel_hi:[1,0,1] neg_lo:[0,0,1] neg_hi:[0,0,1]
	v_pk_mul_f32 v[52:53], v[6:7], v[6:7]
	v_pk_mul_f32 v[24:25], v[24:25], v[68:69] op_sel_hi:[1,0]
	v_pk_fma_f32 v[22:23], v[38:39], v[66:67], v[22:23] op_sel_hi:[1,0,1] neg_lo:[0,0,1] neg_hi:[0,0,1]
	v_add_f32_e32 v0, v36, v0
	v_pk_mul_f32 v[50:51], v[8:9], v[8:9]
	v_pk_fma_f32 v[24:25], v[40:41], v[66:67], v[24:25] op_sel_hi:[1,0,1] neg_lo:[0,0,1] neg_hi:[0,0,1]
	v_pk_fma_f32 v[38:39], v[22:23], v[22:23], v[52:53]
	v_add_f32_e32 v0, v37, v0
	v_pk_fma_f32 v[40:41], v[24:25], v[24:25], v[50:51]
	v_pk_mul_f32 v[50:51], v[58:59], v[68:69] op_sel_hi:[1,0]
	v_add_f32_e32 v0, v38, v0
	v_pk_fma_f32 v[10:11], v[10:11], v[66:67], v[50:51] op_sel_hi:[1,0,1] neg_lo:[0,0,1] neg_hi:[0,0,1]
	v_pk_mul_f32 v[26:27], v[26:27], v[68:69] op_sel_hi:[1,0]
	v_add_f32_e32 v0, v39, v0
	v_pk_mul_f32 v[50:51], v[10:11], v[10:11]
	v_pk_fma_f32 v[26:27], v[42:43], v[66:67], v[26:27] op_sel_hi:[1,0,1] neg_lo:[0,0,1] neg_hi:[0,0,1]
	v_add_f32_e32 v0, v40, v0
	v_pk_fma_f32 v[12:13], v[12:13], v[66:67], v[44:45] op_sel_hi:[1,0,1] neg_lo:[0,0,1] neg_hi:[0,0,1]
	v_pk_mul_f32 v[30:31], v[30:31], v[68:69] op_sel_hi:[1,0]
	v_pk_fma_f32 v[42:43], v[26:27], v[26:27], v[50:51]
	v_add_f32_e32 v0, v41, v0
	v_pk_mul_f32 v[44:45], v[12:13], v[12:13]
	v_pk_fma_f32 v[30:31], v[46:47], v[66:67], v[30:31] op_sel_hi:[1,0,1] neg_lo:[0,0,1] neg_hi:[0,0,1]
	v_pk_mul_f32 v[46:47], v[62:63], v[68:69] op_sel_hi:[1,0]
	v_add_f32_e32 v0, v42, v0
	v_pk_fma_f32 v[44:45], v[28:29], v[28:29], v[44:45]
	v_pk_fma_f32 v[14:15], v[14:15], v[66:67], v[46:47] op_sel_hi:[1,0,1] neg_lo:[0,0,1] neg_hi:[0,0,1]
	v_add_f32_e32 v0, v43, v0
	v_pk_mul_f32 v[46:47], v[14:15], v[14:15]
	v_add_f32_e32 v0, v44, v0
	v_pk_fma_f32 v[46:47], v[30:31], v[30:31], v[46:47]
	v_pk_fma_f32 v[16:17], v[16:17], v[66:67], v[48:49] op_sel_hi:[1,0,1] neg_lo:[0,0,1] neg_hi:[0,0,1]
	v_add_f32_e32 v0, v45, v0
	v_pk_mul_f32 v[48:49], v[16:17], v[16:17]
	v_add_f32_e32 v0, v46, v0
	v_pk_fma_f32 v[48:49], v[32:33], v[32:33], v[48:49]
	v_add_f32_e32 v0, v47, v0
	v_add_f32_e32 v0, v48, v0
	v_add_f32_e32 v0, v49, v0
	ds_bpermute_b32 v34, v64, v0
	v_lshl_add_u64 v[62:63], v[60:61], 0, s[0:1]
	s_mov_b32 s0, 0x8a00000
	s_waitcnt lgkmcnt(0)
	v_add_f32_e32 v0, v0, v34
	v_fmamk_f32 v0, v0, 0x3c800000, v228
	v_rsq_f32_e32 v0, v0
	s_nop 0
	v_mul_f32_e32 v0, v185, v0
	v_pk_mul_f32 v[2:3], v[2:3], v[0:1] op_sel_hi:[1,0]
	v_pk_mul_f32 v[4:5], v[4:5], v[0:1] op_sel_hi:[1,0]
	v_pk_mul_f32 v[18:19], v[18:19], v[0:1] op_sel_hi:[1,0]
	v_pk_mul_f32 v[20:21], v[20:21], v[0:1] op_sel_hi:[1,0]
	v_cvt_pk_bf16_f32 v2, v2, v3
	v_cvt_pk_bf16_f32 v3, v4, v5
	v_add_co_u32_e32 v4, vcc, s0, v60
	v_cvt_pk_bf16_f32 v18, v18, v19
	v_cvt_pk_bf16_f32 v19, v20, v21
	v_addc_co_u32_e32 v5, vcc, 0, v61, vcc
	v_mov_b32_e32 v240, v18
	v_mov_b32_e32 v241, v19
	v_mov_b32_e32 v244, v2
	v_mov_b32_e32 v245, v3
	v_pk_mul_f32 v[2:3], v[22:23], v[0:1] op_sel_hi:[1,0]
	v_pk_mul_f32 v[4:5], v[24:25], v[0:1] op_sel_hi:[1,0]
	v_cvt_pk_bf16_f32 v2, v2, v3
	v_cvt_pk_bf16_f32 v3, v4, v5
	v_pk_mul_f32 v[4:5], v[6:7], v[0:1] op_sel_hi:[1,0]
	v_pk_mul_f32 v[6:7], v[8:9], v[0:1] op_sel_hi:[1,0]
	v_cvt_pk_bf16_f32 v4, v4, v5
	v_cvt_pk_bf16_f32 v5, v6, v7
	v_mov_b32_e32 v242, v2
	v_mov_b32_e32 v243, v3
	v_mbcnt_lo_u32_b32 v222, -1, 0
	v_mbcnt_hi_u32_b32 v222, -1, v222
	v_lshrrev_b32_e32 v222, 5, v222
	v_lshlrev_b32_e32 v222, 3, v222
	v_mov_b32_e32 v223, 0
	v_permlane32_swap_b32_e32 v240, v242
	v_permlane32_swap_b32_e32 v241, v243
	v_lshl_add_u64 v[222:223], v[62:63], 0, v[222:223]
	global_store_dwordx4 v[222:223], v[240:243], off sc1
	v_mov_b32_e32 v246, v4
	v_mov_b32_e32 v247, v5
	v_mbcnt_lo_u32_b32 v222, -1, 0
	v_mbcnt_hi_u32_b32 v222, -1, v222
	v_lshrrev_b32_e32 v222, 5, v222
	v_lshlrev_b32_e32 v222, 3, v222
	v_mov_b32_e32 v223, 0
	v_permlane32_swap_b32_e32 v244, v246
	v_permlane32_swap_b32_e32 v245, v247
	v_lshl_add_u64 v[222:223], v[62:63], 0, v[222:223]
	global_store_dwordx4 v[222:223], v[244:247], off offset:64 sc1
	v_pk_mul_f32 v[2:3], v[26:27], v[0:1] op_sel_hi:[1,0]
	v_pk_mul_f32 v[4:5], v[28:29], v[0:1] op_sel_hi:[1,0]
	v_cvt_pk_bf16_f32 v2, v2, v3
	v_cvt_pk_bf16_f32 v3, v4, v5
	v_pk_mul_f32 v[4:5], v[10:11], v[0:1] op_sel_hi:[1,0]
	v_pk_mul_f32 v[6:7], v[12:13], v[0:1] op_sel_hi:[1,0]
	v_cvt_pk_bf16_f32 v4, v4, v5
	v_cvt_pk_bf16_f32 v5, v6, v7
	v_mov_b32_e32 v240, v2
	v_mov_b32_e32 v241, v3
	v_mov_b32_e32 v244, v4
	v_mov_b32_e32 v245, v5
	v_pk_mul_f32 v[2:3], v[30:31], v[0:1] op_sel_hi:[1,0]
	v_pk_mul_f32 v[4:5], v[32:33], v[0:1] op_sel_hi:[1,0]
	v_cvt_pk_bf16_f32 v2, v2, v3
	v_cvt_pk_bf16_f32 v3, v4, v5
	v_pk_mul_f32 v[4:5], v[14:15], v[0:1] op_sel_hi:[1,0]
	v_pk_mul_f32 v[6:7], v[16:17], v[0:1] op_sel_hi:[1,0]
	v_cvt_pk_bf16_f32 v4, v4, v5
	v_cvt_pk_bf16_f32 v5, v6, v7
	v_mov_b32_e32 v242, v2
	v_mov_b32_e32 v243, v3
	v_mbcnt_lo_u32_b32 v222, -1, 0
	v_mbcnt_hi_u32_b32 v222, -1, v222
	v_lshrrev_b32_e32 v222, 5, v222
	v_lshlrev_b32_e32 v222, 3, v222
	v_mov_b32_e32 v223, 0
	v_permlane32_swap_b32_e32 v240, v242
	v_permlane32_swap_b32_e32 v241, v243
	v_lshl_add_u64 v[222:223], v[62:63], 0, v[222:223]
	global_store_dwordx4 v[222:223], v[240:243], off offset:32 sc1
	v_mov_b32_e32 v246, v4
	v_mov_b32_e32 v247, v5
	v_mbcnt_lo_u32_b32 v222, -1, 0
	v_mbcnt_hi_u32_b32 v222, -1, v222
	v_lshrrev_b32_e32 v222, 5, v222
	v_lshlrev_b32_e32 v222, 3, v222
	v_mov_b32_e32 v223, 0
	v_permlane32_swap_b32_e32 v244, v246
	v_permlane32_swap_b32_e32 v245, v247
	v_lshl_add_u64 v[222:223], v[62:63], 0, v[222:223]
	global_store_dwordx4 v[222:223], v[244:247], off offset:96 sc1
	s_barrier
